# attention block epilogue: 15 diff_norm weight loads hoisted to epilogue start into free registers, removing 15 serialized vmcnt(0) round trips between the output stores
# speedup vs baseline: 1.0107x; 1.0107x over previous
.LBB0_33:
	v_mov_b32_e32 v130, v208
	v_lshrrev_b32_e32 v248, 1, v208
	v_and_b32_e32 v248, 16, v248
	global_load_dwordx4 v[156:159], v248, s[40:41] offset:32
	global_load_dwordx4 v[160:163], v248, s[40:41] offset:64
	global_load_dwordx4 v[164:167], v248, s[40:41] offset:96
	global_load_dwordx4 v[168:171], v248, s[40:41] offset:128
	global_load_dwordx4 v[172:175], v248, s[40:41] offset:160
	global_load_dwordx4 v[176:179], v248, s[40:41] offset:192
	global_load_dwordx4 v[180:183], v248, s[40:41] offset:224
	global_load_dwordx4 v[184:187], v248, s[40:41] offset:256
	global_load_dwordx4 v[216:219], v248, s[40:41] offset:288
	global_load_dwordx4 v[220:223], v248, s[40:41] offset:320
	global_load_dwordx4 v[224:227], v248, s[40:41] offset:352
	global_load_dwordx4 v[228:231], v248, s[40:41] offset:384
	global_load_dwordx4 v[232:235], v248, s[40:41] offset:416
	global_load_dwordx4 v[236:239], v248, s[40:41] offset:448
	global_load_dwordx4 v[240:243], v248, s[40:41] offset:480
	v_and_b32_e32 v131, 64, v214
	v_and_b32_e32 v128, 63, v130
	v_lshlrev_b32_e32 v128, 2, v128
	global_load_dword v129, v128, s[42:43]
	global_load_dword v132, v128, s[44:45]
	global_load_dword v134, v128, s[46:47]
	s_nop 0
	global_load_dword v128, v128, s[50:51]
	v_add_u32_e32 v136, 64, v131
	v_xor_b32_e32 v131, 32, v214
	v_cmp_lt_i32_e32 vcc, v131, v136
	v_readfirstlane_b32 s27, v130
	s_ashr_i32 s86, s27, 1
	v_cndmask_b32_e32 v131, v214, v131, vcc
	v_lshlrev_b32_e32 v131, 2, v131
	s_andn2_b32 s86, s86, 31
	s_mov_b32 s27, 0x5400000
	s_waitcnt vmcnt(2)
	v_mul_f32_e32 v133, v129, v132
	ds_bpermute_b32 v133, v131, v133
	s_waitcnt vmcnt(0)
	v_mul_f32_e32 v135, v134, v128
	ds_bpermute_b32 v135, v131, v135
	s_waitcnt lgkmcnt(1)
	v_fmac_f32_e32 v133, v129, v132
	v_xor_b32_e32 v129, 16, v214
	v_cmp_lt_i32_e32 vcc, v129, v136
	s_waitcnt lgkmcnt(0)
	v_fmac_f32_e32 v135, v134, v128
	v_cndmask_b32_e32 v129, v214, v129, vcc
	v_lshlrev_b32_e32 v129, 2, v129
	ds_bpermute_b32 v132, v129, v133
	ds_bpermute_b32 v128, v129, v135
	s_waitcnt lgkmcnt(1)
	v_add_f32_e32 v132, v133, v132
	v_xor_b32_e32 v133, 8, v214
	v_cmp_lt_i32_e32 vcc, v133, v136
	s_waitcnt lgkmcnt(0)
	v_add_f32_e32 v128, v135, v128
	v_cndmask_b32_e32 v133, v214, v133, vcc
	v_lshlrev_b32_e32 v133, 2, v133
	ds_bpermute_b32 v137, v133, v132
	ds_bpermute_b32 v129, v133, v128
	s_waitcnt lgkmcnt(1)
	v_add_f32_e32 v132, v132, v137
	v_xor_b32_e32 v137, 4, v214
	v_cmp_lt_i32_e32 vcc, v137, v136
	s_waitcnt lgkmcnt(0)
	v_add_f32_e32 v128, v128, v129
	v_cndmask_b32_e32 v137, v214, v137, vcc
	v_lshlrev_b32_e32 v137, 2, v137
	ds_bpermute_b32 v138, v137, v132
	ds_bpermute_b32 v129, v137, v128
	s_waitcnt lgkmcnt(1)
	v_add_f32_e32 v132, v132, v138
	v_xor_b32_e32 v138, 2, v214
	v_cmp_lt_i32_e32 vcc, v138, v136
	s_waitcnt lgkmcnt(0)
	v_add_f32_e32 v128, v128, v129
	v_cndmask_b32_e32 v138, v214, v138, vcc
	v_lshlrev_b32_e32 v138, 2, v138
	ds_bpermute_b32 v139, v138, v132
	ds_bpermute_b32 v129, v138, v128
	s_waitcnt lgkmcnt(1)
	v_add_f32_e32 v132, v132, v139
	v_xor_b32_e32 v139, 1, v214
	v_cmp_lt_i32_e32 vcc, v139, v136
	s_waitcnt lgkmcnt(0)
	v_add_f32_e32 v128, v128, v129
	v_cndmask_b32_e32 v136, v214, v139, vcc
	v_lshlrev_b32_e32 v136, 2, v136
	ds_bpermute_b32 v139, v136, v132
	ds_bpermute_b32 v129, v136, v128
	s_waitcnt lgkmcnt(1)
	v_add_f32_e32 v132, v132, v139
	s_waitcnt lgkmcnt(0)
	v_add_f32_e32 v128, v128, v129
	v_mul_f32_e32 v129, 0x3fb8aa3b, v132
	v_fma_f32 v133, v132, s23, -v129
	v_rndne_f32_e32 v134, v129
	v_fmac_f32_e32 v133, 0x32a5705f, v132
	v_sub_f32_e32 v129, v129, v134
	v_add_f32_e32 v129, v129, v133
	v_exp_f32_e32 v129, v129
	v_cvt_i32_f32_e32 v133, v134
	v_cmp_ngt_f32_e32 vcc, s17, v132
	v_ldexp_f32 v129, v129, v133
	s_nop 0
	v_cndmask_b32_e32 v129, 0, v129, vcc
	v_cmp_nlt_f32_e32 vcc, s21, v132
	v_mul_f32_e32 v132, 0x3fb8aa3b, v128
	v_fma_f32 v133, v128, s23, -v132
	v_rndne_f32_e32 v134, v132
	v_fmac_f32_e32 v133, 0x32a5705f, v128
	v_sub_f32_e32 v132, v132, v134
	v_add_f32_e32 v132, v132, v133
	v_exp_f32_e32 v132, v132
	v_cvt_i32_f32_e32 v133, v134
	v_cndmask_b32_e32 v129, v213, v129, vcc
	v_cmp_ngt_f32_e32 vcc, s17, v128
	v_ldexp_f32 v132, v132, v133
	s_nop 0
	v_cndmask_b32_e32 v132, 0, v132, vcc
	v_cmp_nlt_f32_e32 vcc, s21, v128
	s_nop 1
	v_cndmask_b32_e32 v128, v213, v132, vcc
	v_sub_f32_e32 v128, v129, v128
	v_add_f32_e32 v132, v194, v128
	ds_bpermute_b32 v128, v131, v150
	ds_bpermute_b32 v129, v131, v151
	s_waitcnt lgkmcnt(0)
	v_pk_add_f32 v[128:129], v[150:151], v[128:129]
	s_nop 0
	v_div_scale_f32 v133, s[56:57], v129, v129, v132
	v_rcp_f32_e32 v134, v133
	s_nop 0
	v_fma_f32 v135, -v133, v134, 1.0
	v_fmac_f32_e32 v134, v135, v134
	v_div_scale_f32 v135, vcc, v132, v129, v132
	v_mul_f32_e32 v136, v135, v134
	v_fma_f32 v137, -v133, v136, v135
	v_fmac_f32_e32 v136, v137, v134
	v_fma_f32 v133, -v133, v136, v135
	v_div_fmas_f32 v133, v133, v134, v136
	v_div_fixup_f32 v129, v133, v129, v132
	v_div_scale_f32 v132, s[56:57], v128, v128, 1.0
	v_rcp_f32_e32 v133, v132
	s_mov_b64 s[56:57], 0x5400400
	v_fma_f32 v134, -v132, v133, 1.0
	v_fmac_f32_e32 v133, v134, v133
	v_div_scale_f32 v134, vcc, 1.0, v128, 1.0
	v_mul_f32_e32 v135, v134, v133
	v_fma_f32 v136, -v132, v135, v134
	v_fmac_f32_e32 v135, v136, v133
	v_fma_f32 v132, -v132, v135, v134
	v_div_fmas_f32 v132, v132, v133, v135
	v_div_fixup_f32 v128, v132, v128, 1.0
	v_mov_b32_e32 v133, v96
	v_mov_b32_e32 v96, v113
	v_pk_mul_f32 v[96:97], v[96:97], v[128:129]
	v_mov_b32_e32 v132, v112
	v_sub_f32_e32 v113, v96, v97
	v_mov_b32_e32 v96, v114
	v_mov_b32_e32 v97, v98
	v_pk_mul_f32 v[96:97], v[96:97], v[128:129]
	v_mov_b32_e32 v98, v115
	v_sub_f32_e32 v114, v96, v97
	v_pk_mul_f32 v[96:97], v[98:99], v[128:129]
	v_pk_mul_f32 v[132:133], v[132:133], v[128:129]
	v_sub_f32_e32 v115, v96, v97
	v_mov_b32_e32 v96, v116
	v_mov_b32_e32 v97, v100
	v_pk_mul_f32 v[96:97], v[96:97], v[128:129]
	v_mov_b32_e32 v100, v117
	v_sub_f32_e32 v98, v96, v97
	v_pk_mul_f32 v[96:97], v[100:101], v[128:129]
	v_mov_b32_e32 v116, v124
	v_sub_f32_e32 v99, v96, v97
	v_mov_b32_e32 v96, v118
	v_mov_b32_e32 v97, v102
	v_pk_mul_f32 v[96:97], v[96:97], v[128:129]
	v_mov_b32_e32 v102, v119
	v_sub_f32_e32 v100, v96, v97
	v_pk_mul_f32 v[96:97], v[102:103], v[128:129]
	v_mov_b32_e32 v117, v108
	v_sub_f32_e32 v101, v96, v97
	v_mov_b32_e32 v97, v104
	v_mov_b32_e32 v104, v121
	v_pk_mul_f32 v[102:103], v[104:105], v[128:129]
	v_mov_b32_e32 v105, v106
	v_mov_b32_e32 v106, v123
	v_pk_mul_f32 v[106:107], v[106:107], v[128:129]
	v_pk_mul_f32 v[116:117], v[116:117], v[128:129]
	v_sub_f32_e32 v107, v106, v107
	v_sub_f32_e32 v106, v116, v117
	v_mov_b32_e32 v108, v125
	v_mov_b32_e32 v116, v126
	v_mov_b32_e32 v117, v110
	v_mov_b32_e32 v110, v127
	v_pk_mul_f32 v[108:109], v[108:109], v[128:129]
	v_pk_mul_f32 v[116:117], v[116:117], v[128:129]
	v_pk_mul_f32 v[110:111], v[110:111], v[128:129]
	v_sub_f32_e32 v108, v108, v109
	v_sub_f32_e32 v109, v116, v117
	v_sub_f32_e32 v116, v110, v111
	v_mov_b32_e32 v110, v80
	v_mov_b32_e32 v111, v64
	v_mov_b32_e32 v64, v81
	v_pk_mul_f32 v[110:111], v[110:111], v[128:129]
	v_pk_mul_f32 v[64:65], v[64:65], v[128:129]
	v_mov_b32_e32 v104, v122
	v_sub_f32_e32 v111, v110, v111
	v_sub_f32_e32 v110, v64, v65
	v_mov_b32_e32 v64, v82
	v_mov_b32_e32 v65, v66
	v_pk_mul_f32 v[104:105], v[104:105], v[128:129]
	v_pk_mul_f32 v[64:65], v[64:65], v[128:129]
	v_mov_b32_e32 v66, v83
	v_sub_f32_e32 v104, v104, v105
	v_sub_f32_e32 v105, v64, v65
	v_pk_mul_f32 v[64:65], v[66:67], v[128:129]
	v_mov_b32_e32 v96, v120
	v_sub_f32_e32 v102, v102, v103
	v_sub_f32_e32 v103, v64, v65
	v_mov_b32_e32 v64, v84
	v_mov_b32_e32 v65, v68
	v_pk_mul_f32 v[96:97], v[96:97], v[128:129]
	v_pk_mul_f32 v[64:65], v[64:65], v[128:129]
	v_mov_b32_e32 v68, v85
	v_sub_f32_e32 v97, v96, v97
	v_sub_f32_e32 v96, v64, v65
	v_pk_mul_f32 v[64:65], v[68:69], v[128:129]
	v_sub_f32_e32 v112, v132, v133
	v_sub_f32_e32 v85, v64, v65
	v_mov_b32_e32 v64, v86
	v_mov_b32_e32 v65, v70
	v_pk_mul_f32 v[64:65], v[64:65], v[128:129]
	v_mov_b32_e32 v70, v87
	v_sub_f32_e32 v84, v64, v65
	v_pk_mul_f32 v[64:65], v[70:71], v[128:129]
	s_nop 0
	v_sub_f32_e32 v83, v64, v65
	v_mov_b32_e32 v64, v88
	v_mov_b32_e32 v65, v72
	v_pk_mul_f32 v[64:65], v[64:65], v[128:129]
	v_mov_b32_e32 v72, v89
	v_sub_f32_e32 v82, v64, v65
	v_pk_mul_f32 v[64:65], v[72:73], v[128:129]
	s_nop 0
	v_sub_f32_e32 v81, v64, v65
	v_mov_b32_e32 v64, v90
	v_mov_b32_e32 v65, v74
	v_pk_mul_f32 v[64:65], v[64:65], v[128:129]
	v_mov_b32_e32 v74, v91
	v_sub_f32_e32 v80, v64, v65
	v_pk_mul_f32 v[64:65], v[74:75], v[128:129]
	s_nop 0
	v_sub_f32_e32 v73, v64, v65
	v_mov_b32_e32 v64, v92
	v_mov_b32_e32 v65, v76
	v_pk_mul_f32 v[64:65], v[64:65], v[128:129]
	v_mov_b32_e32 v76, v93
	v_sub_f32_e32 v72, v64, v65
	v_pk_mul_f32 v[64:65], v[76:77], v[128:129]
	s_nop 0
	v_sub_f32_e32 v71, v64, v65
	v_mov_b32_e32 v64, v94
	v_mov_b32_e32 v65, v78
	v_pk_mul_f32 v[64:65], v[64:65], v[128:129]
	v_mov_b32_e32 v78, v95
	v_sub_f32_e32 v70, v64, v65
	v_pk_mul_f32 v[64:65], v[78:79], v[128:129]
	s_nop 0
	v_sub_f32_e32 v69, v64, v65
	v_mov_b32_e32 v65, v32
	v_mov_b32_e32 v32, v49
	v_pk_mul_f32 v[32:33], v[32:33], v[128:129]
	v_mov_b32_e32 v64, v48
	v_sub_f32_e32 v67, v32, v33
	v_mov_b32_e32 v32, v50
	v_mov_b32_e32 v33, v34
	v_pk_mul_f32 v[32:33], v[32:33], v[128:129]
	v_mov_b32_e32 v34, v51
	v_pk_mul_f32 v[64:65], v[64:65], v[128:129]
	v_sub_f32_e32 v66, v32, v33
	v_pk_mul_f32 v[32:33], v[34:35], v[128:129]
	v_sub_f32_e32 v68, v64, v65
	v_sub_f32_e32 v65, v32, v33
	v_mov_b32_e32 v32, v52
	v_mov_b32_e32 v33, v36
	v_pk_mul_f32 v[32:33], v[32:33], v[128:129]
	v_mov_b32_e32 v36, v53
	v_sub_f32_e32 v64, v32, v33
	v_pk_mul_f32 v[32:33], v[36:37], v[128:129]
	s_nop 0
	v_sub_f32_e32 v53, v32, v33
	v_mov_b32_e32 v32, v54
	v_mov_b32_e32 v33, v38
	v_pk_mul_f32 v[32:33], v[32:33], v[128:129]
	v_mov_b32_e32 v38, v55
	v_sub_f32_e32 v52, v32, v33
	v_pk_mul_f32 v[32:33], v[38:39], v[128:129]
	s_nop 0
	v_sub_f32_e32 v51, v32, v33
	v_mov_b32_e32 v32, v56
	v_mov_b32_e32 v33, v40
	v_pk_mul_f32 v[32:33], v[32:33], v[128:129]
	v_mov_b32_e32 v40, v57
	v_sub_f32_e32 v50, v32, v33
	v_pk_mul_f32 v[32:33], v[40:41], v[128:129]
	s_nop 0
	v_sub_f32_e32 v49, v32, v33
	v_mov_b32_e32 v32, v58
	v_mov_b32_e32 v33, v42
	v_pk_mul_f32 v[32:33], v[32:33], v[128:129]
	v_mov_b32_e32 v42, v59
	v_sub_f32_e32 v48, v32, v33
	v_pk_mul_f32 v[32:33], v[42:43], v[128:129]
	s_nop 0
	v_sub_f32_e32 v41, v32, v33
	v_mov_b32_e32 v32, v60
	v_mov_b32_e32 v33, v44
	v_pk_mul_f32 v[32:33], v[32:33], v[128:129]
	v_mov_b32_e32 v44, v61
	v_sub_f32_e32 v40, v32, v33
	v_pk_mul_f32 v[32:33], v[44:45], v[128:129]
	s_nop 0
	v_sub_f32_e32 v39, v32, v33
	v_mov_b32_e32 v32, v62
	v_mov_b32_e32 v33, v46
	v_pk_mul_f32 v[32:33], v[32:33], v[128:129]
	v_mov_b32_e32 v46, v63
	v_sub_f32_e32 v38, v32, v33
	v_pk_mul_f32 v[32:33], v[46:47], v[128:129]
	s_nop 0
	v_sub_f32_e32 v37, v32, v33
	v_mov_b32_e32 v33, v0
	v_mov_b32_e32 v0, v17
	v_pk_mul_f32 v[0:1], v[0:1], v[128:129]
	v_mov_b32_e32 v32, v16
	v_sub_f32_e32 v35, v0, v1
	v_mov_b32_e32 v0, v18
	v_mov_b32_e32 v1, v2
	v_pk_mul_f32 v[0:1], v[0:1], v[128:129]
	v_mov_b32_e32 v2, v19
	v_pk_mul_f32 v[32:33], v[32:33], v[128:129]
	v_sub_f32_e32 v34, v0, v1
	v_pk_mul_f32 v[0:1], v[2:3], v[128:129]
	v_sub_f32_e32 v36, v32, v33
	v_sub_f32_e32 v33, v0, v1
	v_mov_b32_e32 v1, v4
	v_mov_b32_e32 v4, v21
	v_mul_f32_e32 v21, v112, v112
	v_fmac_f32_e32 v21, v113, v113
	v_fmac_f32_e32 v21, v114, v114
	v_fmac_f32_e32 v21, v115, v115
	v_fmac_f32_e32 v21, v98, v98
	v_fmac_f32_e32 v21, v99, v99
	v_fmac_f32_e32 v21, v100, v100
	v_fmac_f32_e32 v21, v101, v101
	v_fmac_f32_e32 v21, v97, v97
	v_fmac_f32_e32 v21, v102, v102
	v_fmac_f32_e32 v21, v104, v104
	v_fmac_f32_e32 v21, v107, v107
	v_fmac_f32_e32 v21, v106, v106
	v_fmac_f32_e32 v21, v108, v108
	v_fmac_f32_e32 v21, v109, v109
	v_fmac_f32_e32 v21, v116, v116
	v_fmac_f32_e32 v21, v111, v111
	v_fmac_f32_e32 v21, v110, v110
	v_fmac_f32_e32 v21, v105, v105
	v_fmac_f32_e32 v21, v103, v103
	v_fmac_f32_e32 v21, v96, v96
	v_fmac_f32_e32 v21, v85, v85
	v_fmac_f32_e32 v21, v84, v84
	v_fmac_f32_e32 v21, v83, v83
	v_fmac_f32_e32 v21, v82, v82
	v_fmac_f32_e32 v21, v81, v81
	v_fmac_f32_e32 v21, v80, v80
	v_fmac_f32_e32 v21, v73, v73
	v_fmac_f32_e32 v21, v72, v72
	v_fmac_f32_e32 v21, v71, v71
	v_fmac_f32_e32 v21, v70, v70
	v_fmac_f32_e32 v21, v69, v69
	v_fmac_f32_e32 v21, v68, v68
	v_fmac_f32_e32 v21, v67, v67
	v_fmac_f32_e32 v21, v66, v66
	v_fmac_f32_e32 v21, v65, v65
	v_fmac_f32_e32 v21, v64, v64
	v_fmac_f32_e32 v21, v53, v53
	v_fmac_f32_e32 v21, v52, v52
	v_fmac_f32_e32 v21, v51, v51
	v_fmac_f32_e32 v21, v50, v50
	v_fmac_f32_e32 v21, v49, v49
	v_fmac_f32_e32 v21, v48, v48
	v_fmac_f32_e32 v21, v41, v41
	v_fmac_f32_e32 v21, v40, v40
	v_mov_b32_e32 v0, v20
	v_fmac_f32_e32 v21, v39, v39
	v_pk_mul_f32 v[0:1], v[0:1], v[128:129]
	v_fmac_f32_e32 v21, v38, v38
	v_sub_f32_e32 v32, v0, v1
	v_pk_mul_f32 v[0:1], v[4:5], v[128:129]
	v_fmac_f32_e32 v21, v37, v37
	v_sub_f32_e32 v20, v0, v1
	v_mov_b32_e32 v0, v22
	v_mov_b32_e32 v1, v6
	v_mov_b32_e32 v6, v23
	v_fmac_f32_e32 v21, v36, v36
	v_pk_mul_f32 v[0:1], v[0:1], v[128:129]
	v_pk_mul_f32 v[2:3], v[6:7], v[128:129]
	v_fmac_f32_e32 v21, v35, v35
	v_mov_b32_e32 v4, v2
	v_mov_b32_e32 v5, v0
	v_mov_b32_e32 v0, v3
	v_mov_b32_e32 v2, v24
	v_mov_b32_e32 v3, v8
	v_mov_b32_e32 v8, v25
	v_fmac_f32_e32 v21, v34, v34
	v_pk_add_f32 v[18:19], v[4:5], v[0:1] neg_lo:[0,1] neg_hi:[0,1]
	v_pk_mul_f32 v[2:3], v[2:3], v[128:129]
	v_pk_mul_f32 v[4:5], v[8:9], v[128:129]
	v_fmac_f32_e32 v21, v33, v33
	v_mov_b32_e32 v6, v4
	v_mov_b32_e32 v7, v2
	v_mov_b32_e32 v2, v5
	v_mov_b32_e32 v4, v26
	v_mov_b32_e32 v5, v10
	v_mov_b32_e32 v10, v27
	v_fmac_f32_e32 v21, v32, v32
	v_pk_mul_f32 v[0:1], v[18:19], v[18:19]
	v_pk_add_f32 v[16:17], v[6:7], v[2:3] neg_lo:[0,1] neg_hi:[0,1]
	v_pk_mul_f32 v[4:5], v[4:5], v[128:129]
	v_pk_mul_f32 v[6:7], v[10:11], v[128:129]
	v_fmac_f32_e32 v21, v20, v20
	v_mov_b32_e32 v8, v6
	v_mov_b32_e32 v9, v4
	v_mov_b32_e32 v4, v7
	v_add_f32_e32 v1, v1, v21
	v_pk_mul_f32 v[2:3], v[16:17], v[16:17]
	v_pk_add_f32 v[8:9], v[8:9], v[4:5] neg_lo:[0,1] neg_hi:[0,1]
	v_mov_b32_e32 v4, v28
	v_mov_b32_e32 v5, v12
	v_mov_b32_e32 v12, v29
	v_add_f32_e32 v0, v0, v1
	v_pk_mul_f32 v[4:5], v[4:5], v[128:129]
	v_pk_mul_f32 v[6:7], v[12:13], v[128:129]
	v_add_f32_e32 v0, v3, v0
	v_pk_mul_f32 v[10:11], v[8:9], v[8:9]
	v_mov_b32_e32 v12, v6
	v_mov_b32_e32 v13, v4
	v_mov_b32_e32 v4, v7
	v_add_f32_e32 v0, v2, v0
	v_pk_add_f32 v[4:5], v[12:13], v[4:5] neg_lo:[0,1] neg_hi:[0,1]
	v_mov_b32_e32 v6, v129
	v_add_f32_e32 v0, v11, v0
	v_pk_mul_f32 v[12:13], v[4:5], v[4:5]
	v_pk_mul_f32 v[6:7], v[14:15], v[6:7] op_sel_hi:[1,0]
	v_add_f32_e32 v0, v10, v0
	v_pk_fma_f32 v[6:7], v[30:31], v[128:129], v[6:7] op_sel_hi:[1,0,1] neg_lo:[0,0,1] neg_hi:[0,0,1]
	v_add_f32_e32 v0, v13, v0
	v_pk_mul_f32 v[14:15], v[6:7], v[6:7]
	v_add_f32_e32 v0, v12, v0
	v_add_f32_e32 v0, v14, v0
	v_add_f32_e32 v0, v15, v0
	ds_bpermute_b32 v1, v131, v0
	s_waitcnt lgkmcnt(0)
	v_add_f32_e32 v0, v0, v1
	v_fmamk_f32 v0, v0, 0x3c000000, v210
	v_cmp_gt_f32_e32 vcc, s89, v0
	v_mul_f32_e32 v1, 0x4b800000, v0
	s_nop 0
	v_cndmask_b32_e32 v0, v0, v1, vcc
	v_rsq_f32_e32 v0, v0
	s_nop 0
	v_mul_f32_e32 v1, 0x45800000, v0
	v_cndmask_b32_e32 v0, v0, v1, vcc
	v_mul_f32_e32 v12, v195, v0
	v_and_or_b32 v0, v130, 31, s53
	v_add_u32_e32 v0, s86, v0
	v_ashrrev_i32_e32 v1, 31, v0
	v_lshlrev_b64 v[0:1], 11, v[0:1]
	v_lshl_add_u64 v[0:1], s[38:39], 0, v[0:1]
	v_lshl_add_u64 v[10:11], v[0:1], 0, s[98:99]
	v_lshrrev_b32_e32 v0, 3, v130
	v_and_b32_e32 v21, 4, v0
	v_lshlrev_b32_e32 v13, 2, v21
	global_load_dwordx4 v[0:3], v13, s[40:41]
	v_mul_f32_e32 v14, v112, v12
	v_lshlrev_b32_e32 v144, 1, v21
	v_mul_f32_e32 v8, v8, v12
	s_mov_b64 s[86:87], 0
	s_waitcnt vmcnt(0)
	v_mul_f32_e32 v0, v0, v14
	v_mul_f32_e32 v14, v113, v12
	v_mul_f32_e32 v1, v1, v14
	s_nop 0
	v_cvt_pk_bf16_f32 v14, v0, v1
	s_nop 1
	v_mul_f32_e32 v0, v114, v12
	v_mul_f32_e32 v1, v115, v12
	v_mul_f32_e32 v0, v2, v0
	v_mul_f32_e32 v1, v3, v1
	v_lshl_add_u64 v[2:3], v[10:11], 0, v[144:145]
	s_nop 0
	v_cvt_pk_bf16_f32 v15, v0, v1
	s_nop 1
	v_lshl_add_u64 v[0:1], v[2:3], 0, s[56:57]
	v_add_co_u32_e32 v2, vcc, s27, v2
	v_mul_f32_e32 v10, v101, v12
	s_nop 0
	v_addc_co_u32_e32 v3, vcc, 0, v3, vcc
	global_store_dwordx2 v[2:3], v[14:15], off offset:1024
	v_mul_f32_e32 v2, v98, v12
	v_mul_f32_e32 v3, v99, v12
	s_and_b64 vcc, exec, s[84:85]
	v_mul_f32_e32 v2, v156, v2
	v_mul_f32_e32 v3, v157, v3
	s_nop 0
	v_cvt_pk_bf16_f32 v2, v2, v3
	s_nop 1
	v_mul_f32_e32 v3, v100, v12
	v_mul_f32_e32 v3, v158, v3
	v_mul_f32_e32 v10, v159, v10
	s_nop 0
	v_cvt_pk_bf16_f32 v3, v3, v10
	s_nop 1
	global_store_dwordx2 v[0:1], v[2:3], off offset:16
	v_mul_f32_e32 v2, v97, v12
	v_mul_f32_e32 v3, v102, v12
	v_mul_f32_e32 v10, v107, v12
	v_mul_f32_e32 v2, v160, v2
	v_mul_f32_e32 v3, v161, v3
	s_nop 0
	v_cvt_pk_bf16_f32 v2, v2, v3
	s_nop 1
	v_mul_f32_e32 v3, v104, v12
	v_mul_f32_e32 v3, v162, v3
	v_mul_f32_e32 v10, v163, v10
	s_nop 0
	v_cvt_pk_bf16_f32 v3, v3, v10
	s_nop 1
	global_store_dwordx2 v[0:1], v[2:3], off offset:32
	v_mul_f32_e32 v2, v106, v12
	v_mul_f32_e32 v3, v108, v12
	v_mul_f32_e32 v10, v116, v12
	v_mul_f32_e32 v2, v164, v2
	v_mul_f32_e32 v3, v165, v3
	s_nop 0
	v_cvt_pk_bf16_f32 v2, v2, v3
	s_nop 1
	v_mul_f32_e32 v3, v109, v12
	v_mul_f32_e32 v3, v166, v3
	v_mul_f32_e32 v10, v167, v10
	s_nop 0
	v_cvt_pk_bf16_f32 v3, v3, v10
	s_nop 1
	global_store_dwordx2 v[0:1], v[2:3], off offset:48
	v_mul_f32_e32 v2, v111, v12
	v_mul_f32_e32 v3, v110, v12
	v_mul_f32_e32 v10, v103, v12
	v_mul_f32_e32 v2, v168, v2
	v_mul_f32_e32 v3, v169, v3
	s_nop 0
	v_cvt_pk_bf16_f32 v2, v2, v3
	s_nop 1
	v_mul_f32_e32 v3, v105, v12
	v_mul_f32_e32 v3, v170, v3
	v_mul_f32_e32 v10, v171, v10
	s_nop 0
	v_cvt_pk_bf16_f32 v3, v3, v10
	s_nop 1
	global_store_dwordx2 v[0:1], v[2:3], off offset:64
	v_mul_f32_e32 v2, v96, v12
	v_mul_f32_e32 v3, v85, v12
	v_mul_f32_e32 v10, v83, v12
	v_mul_f32_e32 v2, v172, v2
	v_mul_f32_e32 v3, v173, v3
	s_nop 0
	v_cvt_pk_bf16_f32 v2, v2, v3
	s_nop 1
	v_mul_f32_e32 v3, v84, v12
	v_mul_f32_e32 v3, v174, v3
	v_mul_f32_e32 v10, v175, v10
	s_nop 0
	v_cvt_pk_bf16_f32 v3, v3, v10
	s_nop 1
	global_store_dwordx2 v[0:1], v[2:3], off offset:80
	v_mul_f32_e32 v2, v82, v12
	v_mul_f32_e32 v3, v81, v12
	v_mul_f32_e32 v10, v73, v12
	v_mul_f32_e32 v2, v176, v2
	v_mul_f32_e32 v3, v177, v3
	s_nop 0
	v_cvt_pk_bf16_f32 v2, v2, v3
	s_nop 1
	v_mul_f32_e32 v3, v80, v12
	v_mul_f32_e32 v3, v178, v3
	v_mul_f32_e32 v10, v179, v10
	s_nop 0
	v_cvt_pk_bf16_f32 v3, v3, v10
	s_nop 1
	global_store_dwordx2 v[0:1], v[2:3], off offset:96
	v_mul_f32_e32 v2, v72, v12
	v_mul_f32_e32 v3, v71, v12
	v_mul_f32_e32 v10, v69, v12
	v_mul_f32_e32 v2, v180, v2
	v_mul_f32_e32 v3, v181, v3
	s_nop 0
	v_cvt_pk_bf16_f32 v2, v2, v3
	s_nop 1
	v_mul_f32_e32 v3, v70, v12
	v_mul_f32_e32 v3, v182, v3
	v_mul_f32_e32 v10, v183, v10
	s_nop 0
	v_cvt_pk_bf16_f32 v3, v3, v10
	s_nop 1
	global_store_dwordx2 v[0:1], v[2:3], off offset:112
	v_mul_f32_e32 v2, v68, v12
	v_mul_f32_e32 v3, v67, v12
	v_mul_f32_e32 v10, v65, v12
	v_mul_f32_e32 v2, v184, v2
	v_mul_f32_e32 v3, v185, v3
	s_nop 0
	v_cvt_pk_bf16_f32 v2, v2, v3
	s_nop 1
	v_mul_f32_e32 v3, v66, v12
	v_mul_f32_e32 v3, v186, v3
	v_mul_f32_e32 v10, v187, v10
	s_nop 0
	v_cvt_pk_bf16_f32 v3, v3, v10
	s_nop 1
	global_store_dwordx2 v[0:1], v[2:3], off offset:128
	v_mul_f32_e32 v2, v64, v12
	v_mul_f32_e32 v3, v53, v12
	v_mul_f32_e32 v10, v51, v12
	v_mul_f32_e32 v2, v216, v2
	v_mul_f32_e32 v3, v217, v3
	s_nop 0
	v_cvt_pk_bf16_f32 v2, v2, v3
	s_nop 1
	v_mul_f32_e32 v3, v52, v12
	v_mul_f32_e32 v3, v218, v3
	v_mul_f32_e32 v10, v219, v10
	s_nop 0
	v_cvt_pk_bf16_f32 v3, v3, v10
	s_nop 1
	global_store_dwordx2 v[0:1], v[2:3], off offset:144
	v_mul_f32_e32 v2, v50, v12
	v_mul_f32_e32 v3, v49, v12
	v_mul_f32_e32 v10, v41, v12
	v_mul_f32_e32 v2, v220, v2
	v_mul_f32_e32 v3, v221, v3
	s_nop 0
	v_cvt_pk_bf16_f32 v2, v2, v3
	s_nop 1
	v_mul_f32_e32 v3, v48, v12
	v_mul_f32_e32 v3, v222, v3
	v_mul_f32_e32 v10, v223, v10
	s_nop 0
	v_cvt_pk_bf16_f32 v3, v3, v10
	s_nop 1
	global_store_dwordx2 v[0:1], v[2:3], off offset:160
	v_mul_f32_e32 v2, v40, v12
	v_mul_f32_e32 v3, v39, v12
	v_mul_f32_e32 v10, v37, v12
	v_mul_f32_e32 v2, v224, v2
	v_mul_f32_e32 v3, v225, v3
	s_nop 0
	v_cvt_pk_bf16_f32 v2, v2, v3
	s_nop 1
	v_mul_f32_e32 v3, v38, v12
	v_mul_f32_e32 v3, v226, v3
	v_mul_f32_e32 v10, v227, v10
	s_nop 0
	v_cvt_pk_bf16_f32 v3, v3, v10
	s_nop 1
	global_store_dwordx2 v[0:1], v[2:3], off offset:176
	v_mul_f32_e32 v2, v36, v12
	v_mul_f32_e32 v3, v35, v12
	v_mul_f32_e32 v10, v33, v12
	v_mul_f32_e32 v2, v228, v2
	v_mul_f32_e32 v3, v229, v3
	s_nop 0
	v_cvt_pk_bf16_f32 v2, v2, v3
	s_nop 1
	v_mul_f32_e32 v3, v34, v12
	v_mul_f32_e32 v3, v230, v3
	v_mul_f32_e32 v10, v231, v10
	s_nop 0
	v_cvt_pk_bf16_f32 v3, v3, v10
	s_nop 1
	global_store_dwordx2 v[0:1], v[2:3], off offset:192
	v_mul_f32_e32 v2, v32, v12
	v_mul_f32_e32 v3, v20, v12
	v_mul_f32_e32 v10, v18, v12
	v_mul_f32_e32 v2, v232, v2
	v_mul_f32_e32 v3, v233, v3
	s_nop 0
	v_cvt_pk_bf16_f32 v2, v2, v3
	s_nop 1
	v_mul_f32_e32 v3, v19, v12
	v_mul_f32_e32 v3, v234, v3
	v_mul_f32_e32 v10, v235, v10
	s_nop 0
	v_cvt_pk_bf16_f32 v3, v3, v10
	s_nop 1
	global_store_dwordx2 v[0:1], v[2:3], off offset:208
	v_mul_f32_e32 v2, v17, v12
	v_mul_f32_e32 v3, v16, v12
	v_mul_f32_e32 v2, v236, v2
	v_mul_f32_e32 v3, v237, v3
	s_nop 0
	v_cvt_pk_bf16_f32 v2, v2, v3
	s_nop 1
	v_mul_f32_e32 v3, v9, v12
	v_mul_f32_e32 v3, v238, v3
	v_mul_f32_e32 v8, v239, v8
	s_nop 0
	v_cvt_pk_bf16_f32 v3, v3, v8
	s_nop 1
	global_store_dwordx2 v[0:1], v[2:3], off offset:224
	v_mul_f32_e32 v2, v5, v12
	v_mul_f32_e32 v3, v4, v12
	v_mul_f32_e32 v4, v7, v12
	v_mul_f32_e32 v2, v240, v2
	v_mul_f32_e32 v3, v241, v3
	s_nop 0
	v_cvt_pk_bf16_f32 v2, v2, v3
	s_nop 1
	v_mul_f32_e32 v3, v6, v12
	v_mul_f32_e32 v3, v242, v3
	v_mul_f32_e32 v4, v243, v4
	s_nop 0
	v_cvt_pk_bf16_f32 v3, v3, v4
	s_nop 1
	global_store_dwordx2 v[0:1], v[2:3], off offset:240
	s_cbranch_vccnz .LBB0_31
